# GATE phase: loads of all four column groups of a row issued together (one wait per row), on top of shared split-K tail reduction and GU epilogue rewrite
# speedup vs baseline: 1.0106x; 1.0106x over previous
; __device__ __forceinline__ float silu_f(float g) { return g * __builtin_amdgcn_rcpf(1.0f + __expf(-g)); }
; __device__ __forceinline__ unsigned pk2(float lo, float hi) { const f32x2_t v = {lo, hi}; return __builtin_bit_cast(unsigned, __builtin_convertvector(v, bf16x2_t)); }
; __device__ __forceinline__ void gla_gate_phase(const float* OG, const bf16* P, const float* gout, bf16* GA, int gw, int NGW, int lane) {
;     for (int row = gw; row < M; row += NGW) {
; #pragma unroll
;         for (int j = 0; j < 4; ++j) {
;             const f32x4 o = *((const f32x4*)(OG + (size_t)row * 1024 + 256 * j) + lane);
;             const float ss = wave_sum((o[0] * o[0] + o[1] * o[1]) + (o[2] * o[2] + o[3] * o[3]));
;             const float r = __builtin_amdgcn_rsqf(ss * (1.0f / 256.0f) + 1e-6f);
;             const f32x4 g = *((const f32x4*)(gout + 256 * j) + lane);
;             const v2u rr = *((const v2u*)(P + (size_t)row * 3072 + 2048 + 256 * j) + lane);
;             const float r0 = bflo(rr.x), r1 = bfhi(rr.x), r2 = bflo(rr.y), r3 = bfhi(rr.y);
;             const float y0 = o[0] * r * g[0] * pg8::silu_f(r0), y1 = o[1] * r * g[1] * pg8::silu_f(r1), y2 = o[2] * r * g[2] * pg8::silu_f(r2), y3 = o[3] * r * g[3] * pg8::silu_f(r3);
;             v2u w; w.x = pk2(y0, y1); w.y = pk2(y2, y3);
;             *((v2u*)(GA + (size_t)row * 1024 + 256 * j) + lane) = w;
;         }
;     }
.LBB0_757:
	v_lshl_add_u64 v[4:5], s[6:7], 0, v[210:211]
	s_mov_b32 s10, 0x9001000
	v_add_co_u32_e32 v6, vcc, s10, v4
	v_lshl_add_u64 v[22:23], s[8:9], 0, v[210:211]
	global_load_dwordx4 v[14:17], v[2:3], off
	global_load_dwordx4 v[18:21], v[0:1], off
	v_addc_co_u32_e32 v7, vcc, 0, v5, vcc
	s_mov_b32 s10, 0x15700000
	v_add_co_u32_e32 v4, vcc, s10, v22
	s_add_i32 s3, s3, s56
	s_nop 0
	v_addc_co_u32_e32 v5, vcc, 0, v23, vcc
	global_load_dwordx2 v[22:23], v[6:7], off
	s_mul_i32 s10, s56, 0x1800
	s_add_u32 s6, s6, s10
	s_addc_u32 s7, s7, s46
	s_add_u32 s8, s8, s60
	s_addc_u32 s9, s9, s61
	s_cmpk_gt_i32 s3, 0x407f
	global_load_dwordx4 v[36:39], v[2:3], off offset:1024
	global_load_dwordx2 v[48:49], v[6:7], off offset:512
	global_load_dwordx4 v[52:55], v[0:1], off offset:1024
	global_load_dwordx4 v[40:43], v[2:3], off offset:2048
	global_load_dwordx2 v[56:57], v[6:7], off offset:1024
	global_load_dwordx4 v[58:61], v[0:1], off offset:2048
	global_load_dwordx4 v[44:47], v[2:3], off offset:3072
	global_load_dwordx2 v[62:63], v[6:7], off offset:1536
	global_load_dwordx4 v[64:67], v[0:1], off offset:3072
	s_waitcnt vmcnt(0)
	v_pk_mul_f32 v[24:25], v[16:17], v[16:17]
	v_pk_mul_f32 v[26:27], v[14:15], v[14:15]
	s_nop 0
	v_pk_mov_b32 v[28:29], v[26:27], v[24:25] op_sel:[1,0]
	v_mov_b32_e32 v27, v25
	v_pk_add_f32 v[24:25], v[28:29], v[26:27]
	v_lshlrev_b32_e32 v26, 16, v22
	v_and_b32_e32 v27, 0xffff0000, v22
	v_lshlrev_b32_e32 v22, 16, v23
	v_and_b32_e32 v23, 0xffff0000, v23
	v_add_f32_e32 v24, v24, v25
	v_mul_f32_e32 v25, 0xbfb8aa3b, v26
	v_mul_f32_e32 v28, 0xbfb8aa3b, v27
	v_mul_f32_e32 v29, 0xbfb8aa3b, v22
	v_mul_f32_e32 v30, 0xbfb8aa3b, v23
	ds_bpermute_b32 v31, v8, v24
	v_exp_f32_e32 v25, v25
	v_exp_f32_e32 v28, v28
	v_exp_f32_e32 v29, v29
	v_exp_f32_e32 v30, v30
	v_add_f32_e32 v25, 1.0, v25
	v_add_f32_e32 v28, 1.0, v28
	v_add_f32_e32 v29, 1.0, v29
	v_add_f32_e32 v30, 1.0, v30
	s_waitcnt lgkmcnt(0)
	v_add_f32_e32 v31, v24, v31
	v_rcp_f32_e32 v24, v25
	v_rcp_f32_e32 v25, v28
	v_rcp_f32_e32 v28, v29
	v_rcp_f32_e32 v29, v30
	ds_bpermute_b32 v30, v9, v31
	v_pk_mul_f32 v[24:25], v[24:25], v[26:27]
	v_pk_mul_f32 v[22:23], v[28:29], v[22:23]
	s_waitcnt lgkmcnt(0)
	v_add_f32_e32 v26, v31, v30
	ds_bpermute_b32 v27, v10, v26
	s_waitcnt lgkmcnt(0)
	v_add_f32_e32 v26, v26, v27
	ds_bpermute_b32 v27, v11, v26
	s_waitcnt lgkmcnt(0)
	v_add_f32_e32 v26, v26, v27
	ds_bpermute_b32 v27, v12, v26
	s_waitcnt lgkmcnt(0)
	v_add_f32_e32 v26, v26, v27
	ds_bpermute_b32 v27, v13, v26
	s_waitcnt lgkmcnt(0)
	v_add_f32_e32 v26, v26, v27
	v_fmamk_f32 v26, v26, 0x3b800000, v209
	v_rsq_f32_e32 v26, v26
	s_nop 0
	v_pk_mul_f32 v[14:15], v[14:15], v[26:27] op_sel_hi:[1,0]
	v_pk_mul_f32 v[16:17], v[16:17], v[26:27] op_sel_hi:[1,0]
	v_pk_mul_f32 v[14:15], v[18:19], v[14:15]
	v_pk_mul_f32 v[16:17], v[20:21], v[16:17]
	v_pk_mul_f32 v[14:15], v[14:15], v[24:25]
	v_pk_mul_f32 v[16:17], v[16:17], v[22:23]
	v_cvt_pk_bf16_f32 v14, v14, v15
	v_cvt_pk_bf16_f32 v15, v16, v17
	global_store_dwordx2 v[4:5], v[14:15], off
	s_nop 0
	v_pk_mul_f32 v[24:25], v[38:39], v[38:39]
	v_pk_mul_f32 v[26:27], v[36:37], v[36:37]
	v_lshlrev_b32_e32 v28, 16, v48
	v_pk_mov_b32 v[30:31], v[26:27], v[24:25] op_sel:[1,0]
	v_mov_b32_e32 v27, v25
	v_and_b32_e32 v29, 0xffff0000, v48
	v_mul_f32_e32 v32, 0xbfb8aa3b, v28
	v_pk_add_f32 v[24:25], v[30:31], v[26:27]
	v_lshlrev_b32_e32 v48, 16, v49
	v_mul_f32_e32 v33, 0xbfb8aa3b, v29
	v_exp_f32_e32 v26, v32
	v_add_f32_e32 v32, v24, v25
	v_and_b32_e32 v49, 0xffff0000, v49
	v_mul_f32_e32 v34, 0xbfb8aa3b, v48
	v_exp_f32_e32 v27, v33
	ds_bpermute_b32 v33, v8, v32
	v_mul_f32_e32 v35, 0xbfb8aa3b, v49
	v_exp_f32_e32 v30, v34
	v_exp_f32_e32 v31, v35
	v_add_f32_e32 v24, 1.0, v26
	v_add_f32_e32 v25, 1.0, v27
	v_add_f32_e32 v26, 1.0, v30
	s_waitcnt lgkmcnt(0)
	v_add_f32_e32 v30, v32, v33
	v_add_f32_e32 v27, 1.0, v31
	ds_bpermute_b32 v31, v9, v30
	v_rcp_f32_e32 v26, v26
	v_rcp_f32_e32 v27, v27
	v_rcp_f32_e32 v24, v24
	v_rcp_f32_e32 v25, v25
	v_pk_mul_f32 v[48:49], v[26:27], v[48:49]
	s_waitcnt lgkmcnt(0)
	v_add_f32_e32 v26, v30, v31
	ds_bpermute_b32 v27, v10, v26
	v_pk_mul_f32 v[24:25], v[24:25], v[28:29]
	s_waitcnt lgkmcnt(0)
	v_add_f32_e32 v26, v26, v27
	ds_bpermute_b32 v27, v11, v26
	s_waitcnt lgkmcnt(0)
	v_add_f32_e32 v26, v26, v27
	ds_bpermute_b32 v27, v12, v26
	s_waitcnt lgkmcnt(0)
	v_add_f32_e32 v26, v26, v27
	ds_bpermute_b32 v27, v13, v26
	s_waitcnt lgkmcnt(0)
; __device__ __forceinline__ float silu_f(float g) { return g * __builtin_amdgcn_rcpf(1.0f + __expf(-g)); }
; __device__ __forceinline__ unsigned pk2(float lo, float hi) { const f32x2_t v = {lo, hi}; return __builtin_bit_cast(unsigned, __builtin_convertvector(v, bf16x2_t)); }
; __device__ __forceinline__ void gla_gate_phase(const float* OG, const bf16* P, const float* gout, bf16* GA, int gw, int NGW, int lane) {
;     for (int row = gw; row < M; row += NGW) {
; #pragma unroll
;         for (int j = 0; j < 4; ++j) {
;             const f32x4 o = *((const f32x4*)(OG + (size_t)row * 1024 + 256 * j) + lane);
;             const float ss = wave_sum((o[0] * o[0] + o[1] * o[1]) + (o[2] * o[2] + o[3] * o[3]));
;             const float r = __builtin_amdgcn_rsqf(ss * (1.0f / 256.0f) + 1e-6f);
;             const f32x4 g = *((const f32x4*)(gout + 256 * j) + lane);
;             const v2u rr = *((const v2u*)(P + (size_t)row * 3072 + 2048 + 256 * j) + lane);
;             const float r0 = bflo(rr.x), r1 = bfhi(rr.x), r2 = bflo(rr.y), r3 = bfhi(rr.y);
;             const float y0 = o[0] * r * g[0] * pg8::silu_f(r0), y1 = o[1] * r * g[1] * pg8::silu_f(r1), y2 = o[2] * r * g[2] * pg8::silu_f(r2), y3 = o[3] * r * g[3] * pg8::silu_f(r3);
;             v2u w; w.x = pk2(y0, y1); w.y = pk2(y2, y3);
;             *((v2u*)(GA + (size_t)row * 1024 + 256 * j) + lane) = w;
;         }
;     }
	v_add_f32_e32 v26, v26, v27
	v_fmamk_f32 v26, v26, 0x3b800000, v209
	v_rsq_f32_e32 v26, v26
	s_nop 0
	v_pk_mul_f32 v[36:37], v[36:37], v[26:27] op_sel_hi:[1,0]
	v_pk_mul_f32 v[38:39], v[38:39], v[26:27] op_sel_hi:[1,0]
	v_pk_mul_f32 v[36:37], v[52:53], v[36:37]
	v_pk_mul_f32 v[38:39], v[54:55], v[38:39]
	v_pk_mul_f32 v[36:37], v[36:37], v[24:25]
	v_pk_mul_f32 v[38:39], v[38:39], v[48:49]
	v_cvt_pk_bf16_f32 v36, v36, v37
	v_cvt_pk_bf16_f32 v37, v38, v39
	global_store_dwordx2 v[4:5], v[36:37], off offset:512
	s_nop 0
	v_pk_mul_f32 v[24:25], v[42:43], v[42:43]
	v_pk_mul_f32 v[26:27], v[40:41], v[40:41]
	v_lshlrev_b32_e32 v28, 16, v56
	v_pk_mov_b32 v[30:31], v[26:27], v[24:25] op_sel:[1,0]
	v_mov_b32_e32 v27, v25
	v_and_b32_e32 v29, 0xffff0000, v56
	v_mul_f32_e32 v32, 0xbfb8aa3b, v28
	v_pk_add_f32 v[24:25], v[30:31], v[26:27]
	v_lshlrev_b32_e32 v56, 16, v57
	v_mul_f32_e32 v33, 0xbfb8aa3b, v29
	v_exp_f32_e32 v26, v32
	v_add_f32_e32 v32, v24, v25
	v_and_b32_e32 v57, 0xffff0000, v57
	v_mul_f32_e32 v34, 0xbfb8aa3b, v56
	v_exp_f32_e32 v27, v33
	ds_bpermute_b32 v33, v8, v32
	v_mul_f32_e32 v35, 0xbfb8aa3b, v57
	v_exp_f32_e32 v30, v34
	v_exp_f32_e32 v31, v35
	v_add_f32_e32 v24, 1.0, v26
	v_add_f32_e32 v25, 1.0, v27
	v_add_f32_e32 v26, 1.0, v30
	s_waitcnt lgkmcnt(0)
	v_add_f32_e32 v30, v32, v33
	v_add_f32_e32 v27, 1.0, v31
	ds_bpermute_b32 v31, v9, v30
	v_rcp_f32_e32 v26, v26
	v_rcp_f32_e32 v27, v27
	v_rcp_f32_e32 v24, v24
	v_rcp_f32_e32 v25, v25
	v_pk_mul_f32 v[56:57], v[26:27], v[56:57]
	s_waitcnt lgkmcnt(0)
	v_add_f32_e32 v26, v30, v31
	ds_bpermute_b32 v27, v10, v26
	v_pk_mul_f32 v[24:25], v[24:25], v[28:29]
	s_waitcnt lgkmcnt(0)
	v_add_f32_e32 v26, v26, v27
	ds_bpermute_b32 v27, v11, v26
	s_waitcnt lgkmcnt(0)
	v_add_f32_e32 v26, v26, v27
	ds_bpermute_b32 v27, v12, v26
	s_waitcnt lgkmcnt(0)
	v_add_f32_e32 v26, v26, v27
	ds_bpermute_b32 v27, v13, v26
	s_waitcnt lgkmcnt(0)
	v_add_f32_e32 v26, v26, v27
	v_fmamk_f32 v26, v26, 0x3b800000, v209
	v_rsq_f32_e32 v26, v26
	s_nop 0
	v_pk_mul_f32 v[40:41], v[40:41], v[26:27] op_sel_hi:[1,0]
	v_pk_mul_f32 v[42:43], v[42:43], v[26:27] op_sel_hi:[1,0]
	v_pk_mul_f32 v[40:41], v[58:59], v[40:41]
	v_pk_mul_f32 v[42:43], v[60:61], v[42:43]
	v_pk_mul_f32 v[40:41], v[40:41], v[24:25]
	v_pk_mul_f32 v[42:43], v[42:43], v[56:57]
	v_cvt_pk_bf16_f32 v40, v40, v41
	v_cvt_pk_bf16_f32 v41, v42, v43
	global_store_dwordx2 v[4:5], v[40:41], off offset:1024
	s_nop 0
	s_nop 0
	v_lshl_add_u64 v[2:3], v[2:3], 0, s[48:49]
	v_pk_mul_f32 v[22:23], v[46:47], v[46:47]
	v_pk_mul_f32 v[24:25], v[44:45], v[44:45]
	v_lshlrev_b32_e32 v26, 16, v62
	v_pk_mov_b32 v[28:29], v[24:25], v[22:23] op_sel:[1,0]
	v_mov_b32_e32 v25, v23
	v_and_b32_e32 v27, 0xffff0000, v62
	v_mul_f32_e32 v30, 0xbfb8aa3b, v26
	v_pk_add_f32 v[22:23], v[28:29], v[24:25]
	v_lshlrev_b32_e32 v62, 16, v63
	v_mul_f32_e32 v31, 0xbfb8aa3b, v27
	v_exp_f32_e32 v24, v30
	v_add_f32_e32 v30, v22, v23
	v_and_b32_e32 v63, 0xffff0000, v63
	v_mul_f32_e32 v32, 0xbfb8aa3b, v62
	v_exp_f32_e32 v25, v31
	ds_bpermute_b32 v31, v8, v30
	v_mul_f32_e32 v33, 0xbfb8aa3b, v63
	v_exp_f32_e32 v28, v32
	v_exp_f32_e32 v29, v33
	v_add_f32_e32 v22, 1.0, v24
	v_add_f32_e32 v23, 1.0, v25
	v_add_f32_e32 v24, 1.0, v28
	s_waitcnt lgkmcnt(0)
	v_add_f32_e32 v28, v30, v31
	v_add_f32_e32 v25, 1.0, v29
	ds_bpermute_b32 v29, v9, v28
	v_rcp_f32_e32 v24, v24
	v_rcp_f32_e32 v25, v25
	v_rcp_f32_e32 v22, v22
	v_rcp_f32_e32 v23, v23
	v_pk_mul_f32 v[62:63], v[24:25], v[62:63]
	s_waitcnt lgkmcnt(0)
	v_add_f32_e32 v24, v28, v29
	ds_bpermute_b32 v25, v10, v24
	v_pk_mul_f32 v[22:23], v[22:23], v[26:27]
	s_waitcnt lgkmcnt(0)
	v_add_f32_e32 v24, v24, v25
	ds_bpermute_b32 v25, v11, v24
	s_waitcnt lgkmcnt(0)
	v_add_f32_e32 v24, v24, v25
	ds_bpermute_b32 v25, v12, v24
	s_waitcnt lgkmcnt(0)
	v_add_f32_e32 v24, v24, v25
	ds_bpermute_b32 v25, v13, v24
	s_waitcnt lgkmcnt(0)
	v_add_f32_e32 v24, v24, v25
	v_fmamk_f32 v24, v24, 0x3b800000, v209
	v_rsq_f32_e32 v24, v24
	s_nop 0
	v_pk_mul_f32 v[44:45], v[44:45], v[24:25] op_sel_hi:[1,0]
	v_pk_mul_f32 v[46:47], v[46:47], v[24:25] op_sel_hi:[1,0]
	v_pk_mul_f32 v[44:45], v[64:65], v[44:45]
	v_pk_mul_f32 v[46:47], v[66:67], v[46:47]
	v_pk_mul_f32 v[44:45], v[44:45], v[22:23]
	v_pk_mul_f32 v[62:63], v[46:47], v[62:63]
	v_cvt_pk_bf16_f32 v44, v44, v45
	v_cvt_pk_bf16_f32 v45, v62, v63
	global_store_dwordx2 v[4:5], v[44:45], off offset:1536
	s_cbranch_scc0 .LBB0_757
